# compress_unit K-loop: 18 loads per iteration issued together instead of load-wait-MFMA chains
# speedup vs baseline: 1.0970x; 1.0082x over previous
.LBB0_343:
	v_ashrrev_i32_e32 v40, 1, v58
	v_mad_i64_i32 v[40:41], s[22:23], v40, s63, v[36:37]
	v_add_u32_e32 v59, 1, v58
	v_ashrrev_i32_e32 v59, 1, v59
	v_mad_i64_i32 v[42:43], s[22:23], v59, s63, v[36:37]
	global_load_dwordx4 v[60:63], v[40:41], off
	global_load_dwordx4 v[64:67], v[42:43], off offset:64
	v_lshl_add_u64 v[44:45], v[38:39], 0, s[12:13]
	s_mov_b32 s14, 0x3100000
	v_add_co_u32_e32 v132, vcc, s14, v44
	s_nop 1
	v_addc_co_u32_e32 v133, vcc, 0, v45, vcc
	global_load_dwordx4 v[68:71], v[132:133], off
	global_load_dwordx4 v[100:103], v[132:133], off offset:64
	s_mov_b32 s14, 0x3110000
	v_add_co_u32_e32 v134, vcc, s14, v44
	s_nop 1
	v_addc_co_u32_e32 v135, vcc, 0, v45, vcc
	global_load_dwordx4 v[72:75], v[134:135], off
	global_load_dwordx4 v[104:107], v[134:135], off offset:64
	s_mov_b32 s14, 0x3120000
	v_add_co_u32_e32 v136, vcc, s14, v44
	s_nop 1
	v_addc_co_u32_e32 v137, vcc, 0, v45, vcc
	global_load_dwordx4 v[76:79], v[136:137], off
	global_load_dwordx4 v[108:111], v[136:137], off offset:64
	s_mov_b32 s14, 0x3130000
	v_add_co_u32_e32 v138, vcc, s14, v44
	s_nop 1
	v_addc_co_u32_e32 v139, vcc, 0, v45, vcc
	global_load_dwordx4 v[80:83], v[138:139], off
	global_load_dwordx4 v[112:115], v[138:139], off offset:64
	s_mov_b32 s14, 0x3140000
	v_add_co_u32_e32 v140, vcc, s14, v44
	s_nop 1
	v_addc_co_u32_e32 v141, vcc, 0, v45, vcc
	global_load_dwordx4 v[84:87], v[140:141], off
	global_load_dwordx4 v[116:119], v[140:141], off offset:64
	s_mov_b32 s14, 0x3150000
	v_add_co_u32_e32 v142, vcc, s14, v44
	s_nop 1
	v_addc_co_u32_e32 v143, vcc, 0, v45, vcc
	global_load_dwordx4 v[88:91], v[142:143], off
	global_load_dwordx4 v[120:123], v[142:143], off offset:64
	s_mov_b32 s14, 0x3160000
	v_add_co_u32_e32 v144, vcc, s14, v44
	s_nop 1
	v_addc_co_u32_e32 v145, vcc, 0, v45, vcc
	global_load_dwordx4 v[92:95], v[144:145], off
	global_load_dwordx4 v[124:127], v[144:145], off offset:64
	s_mov_b32 s14, 0x3170000
	v_add_co_u32_e32 v146, vcc, s14, v44
	s_nop 1
	v_addc_co_u32_e32 v147, vcc, 0, v45, vcc
	global_load_dwordx4 v[96:99], v[146:147], off
	global_load_dwordx4 v[128:131], v[146:147], off offset:64
	s_add_u32 s12, s12, 0x80
	s_addc_u32 s13, s13, 0
	v_add_u32_e32 v58, 2, v58
	s_waitcnt vmcnt(15)
	v_mfma_f32_16x16x32_bf16 v[0:3], v[60:63], v[68:71], v[0:3]
	s_waitcnt vmcnt(13)
	v_mfma_f32_16x16x32_bf16 v[4:7], v[60:63], v[72:75], v[4:7]
	s_waitcnt vmcnt(11)
	v_mfma_f32_16x16x32_bf16 v[8:11], v[60:63], v[76:79], v[8:11]
	s_waitcnt vmcnt(9)
	v_mfma_f32_16x16x32_bf16 v[12:15], v[60:63], v[80:83], v[12:15]
	s_waitcnt vmcnt(7)
	v_mfma_f32_16x16x32_bf16 v[16:19], v[60:63], v[84:87], v[16:19]
	s_waitcnt vmcnt(5)
	v_mfma_f32_16x16x32_bf16 v[20:23], v[60:63], v[88:91], v[20:23]
	s_waitcnt vmcnt(3)
	v_mfma_f32_16x16x32_bf16 v[24:27], v[60:63], v[92:95], v[24:27]
	s_waitcnt vmcnt(1)
	v_mfma_f32_16x16x32_bf16 v[28:31], v[60:63], v[96:99], v[28:31]
	s_waitcnt vmcnt(0)
	v_mfma_f32_16x16x32_bf16 v[0:3], v[64:67], v[100:103], v[0:3]
	v_mfma_f32_16x16x32_bf16 v[4:7], v[64:67], v[104:107], v[4:7]
	v_mfma_f32_16x16x32_bf16 v[8:11], v[64:67], v[108:111], v[8:11]
	v_mfma_f32_16x16x32_bf16 v[12:15], v[64:67], v[112:115], v[12:15]
	v_mfma_f32_16x16x32_bf16 v[16:19], v[64:67], v[116:119], v[16:19]
	v_mfma_f32_16x16x32_bf16 v[20:23], v[64:67], v[120:123], v[20:23]
	v_mfma_f32_16x16x32_bf16 v[24:27], v[64:67], v[124:127], v[24:27]
	v_mfma_f32_16x16x32_bf16 v[28:31], v[64:67], v[128:131], v[28:31]
	s_cmpk_eq_i32 s12, 0x400
	s_cbranch_scc0 .LBB0_343
	s_or_b32 s12, s20, s17
	s_ashr_i32 s13, s12, 31
	s_lshl_b64 s[20:21], s[12:13], 14
	s_lshl_b32 s22, s12, 7
	v_readlane_b32 s12, v253, 47
	s_add_u32 s12, s12, s20
	v_readlane_b32 s13, v253, 48
	s_addc_u32 s13, s13, s21
	s_ashr_i32 s23, s22, 31
	v_lshlrev_b32_e32 v36, 2, v35
	v_lshlrev_b32_e32 v37, 11, v33
	v_lshlrev_b32_e32 v38, 9, v57
	s_lshl_b64 s[20:21], s[22:23], 2
	v_readlane_b32 s22, v253, 49
	v_or3_b32 v37, v37, v38, v36
	v_readlane_b32 s23, v253, 50
	s_add_u32 s20, s22, s20
	ds_write2_b32 v37, v0, v4 offset1:16
	ds_write2_b32 v37, v1, v5 offset0:128 offset1:144
	v_add_u32_e32 v0, 0x400, v37
	s_addc_u32 s21, s23, s21
	v_lshlrev_b32_e32 v5, 5, v35
	ds_write2_b32 v0, v2, v6 offset1:16
	ds_write2_b32 v0, v3, v7 offset0:128 offset1:144
	ds_write2_b32 v37, v8, v12 offset0:32 offset1:48
	ds_write2_b32 v37, v9, v13 offset0:160 offset1:176
	ds_write2_b32 v0, v10, v14 offset0:32 offset1:48
	ds_write2_b32 v0, v11, v15 offset0:160 offset1:176
	ds_write2_b32 v37, v16, v20 offset0:64 offset1:80
	ds_write2_b32 v37, v17, v21 offset0:192 offset1:208
	ds_write2_b32 v0, v18, v22 offset0:64 offset1:80
	ds_write2_b32 v0, v19, v23 offset0:192 offset1:208
	ds_write2_b32 v37, v24, v28 offset0:96 offset1:112
	ds_write2_b32 v37, v25, v29 offset0:224 offset1:240
	ds_write2_b32 v0, v26, v30 offset0:96 offset1:112
	ds_write2_b32 v0, v27, v31 offset0:224 offset1:240
	s_waitcnt lgkmcnt(0)
	s_barrier
	global_load_dwordx4 v[0:3], v5, s[20:21] offset:16
	global_load_dwordx4 v[6:9], v5, s[20:21]
	v_ashrrev_i32_e32 v4, 4, v56
	v_lshl_or_b32 v5, v4, 9, v5
	ds_read_b128 v[10:13], v5
	ds_read_b128 v[14:17], v5 offset:16
	s_movk_i32 s14, 0x110
	v_lshlrev_b32_e32 v152, 1, v34
	s_waitcnt vmcnt(1) lgkmcnt(0)
	v_add_f32_e32 v14, v0, v14
	s_waitcnt vmcnt(0)
	v_add_f32_e32 v10, v6, v10
	v_add_f32_e32 v11, v7, v11
	v_add_f32_e32 v12, v8, v12
	v_add_f32_e32 v13, v9, v13
	v_add_f32_e32 v15, v1, v15
	v_add_f32_e32 v16, v2, v16
	v_add_f32_e32 v17, v3, v17
	ds_read_b128 v[0:3], v5 offset:8192
	ds_read_b128 v[6:9], v5 offset:8208
	s_waitcnt lgkmcnt(1)
	v_add_f32_e32 v10, v10, v0
	v_add_f32_e32 v11, v11, v1
	v_add_f32_e32 v12, v12, v2
	v_add_f32_e32 v13, v13, v3
	s_waitcnt lgkmcnt(0)
	v_add_f32_e32 v14, v14, v6
	v_add_f32_e32 v15, v15, v7
	v_add_f32_e32 v16, v16, v8
	v_add_f32_e32 v17, v17, v9
	ds_read_b128 v[0:3], v5 offset:16384
	ds_read_b128 v[6:9], v5 offset:16400
	s_waitcnt lgkmcnt(1)
	v_add_f32_e32 v10, v10, v0
	v_add_f32_e32 v11, v11, v1
	v_add_f32_e32 v12, v12, v2
	v_add_f32_e32 v13, v13, v3
	s_waitcnt lgkmcnt(0)
	v_add_f32_e32 v14, v14, v6
	v_add_f32_e32 v15, v15, v7
	v_add_f32_e32 v16, v16, v8
	v_add_f32_e32 v17, v17, v9
	ds_read_b128 v[0:3], v5 offset:24576
	ds_read_b128 v[6:9], v5 offset:24592
	s_waitcnt lgkmcnt(1)
	v_add_f32_e32 v0, v10, v0
	v_add_f32_e32 v10, v12, v2
	s_waitcnt lgkmcnt(0)
	v_add_f32_e32 v2, v15, v7
	v_mul_f32_e32 v7, 0x3d372713, v0
	v_mul_f32_e32 v7, v0, v7
	v_fma_f32 v7, v0, v7, v0
	v_mul_f32_e32 v7, 0x3f4c422a, v7
	v_add_f32_e32 v7, v7, v7
	v_mul_f32_e32 v7, 0x3fb8aa3b, v7
	v_exp_f32_e32 v7, v7
	v_add_f32_e32 v5, v16, v8
	v_add_f32_e32 v1, v11, v1
	v_add_f32_e32 v11, v13, v3
	v_add_f32_e32 v7, 1.0, v7
	v_div_scale_f32 v8, s[20:21], v7, v7, 2.0
	v_add_f32_e32 v3, v17, v9
	v_rcp_f32_e32 v9, v8
	v_add_f32_e32 v6, v14, v6
	v_mul_f32_e32 v0, 0.5, v0
	v_mad_u32_u24 v16, v35, s14, v152
	v_fma_f32 v12, -v8, v9, 1.0
	v_fmac_f32_e32 v9, v12, v9
	v_div_scale_f32 v12, vcc, 2.0, v7, 2.0
	v_mul_f32_e32 v13, v12, v9
	v_fma_f32 v14, -v8, v13, v12
	v_fmac_f32_e32 v13, v14, v9
	v_fma_f32 v8, -v8, v13, v12
	v_div_fmas_f32 v8, v8, v9, v13
	v_div_fixup_f32 v7, v8, v7, 2.0
	v_sub_f32_e32 v7, 1.0, v7
	v_add_f32_e32 v7, 1.0, v7
	v_mul_f32_e32 v0, v0, v7
	v_mul_f32_e32 v7, 0x3d372713, v1
	v_mul_f32_e32 v7, v1, v7
	v_fma_f32 v7, v1, v7, v1
	v_mul_f32_e32 v7, 0x3f4c422a, v7
	v_add_f32_e32 v7, v7, v7
	v_mul_f32_e32 v7, 0x3fb8aa3b, v7
	v_exp_f32_e32 v7, v7
	v_mul_f32_e32 v1, 0.5, v1
	v_add_f32_e32 v7, 1.0, v7
	v_div_scale_f32 v8, s[20:21], v7, v7, 2.0
	v_rcp_f32_e32 v9, v8
	s_nop 0
	v_fma_f32 v12, -v8, v9, 1.0
	v_fmac_f32_e32 v9, v12, v9
	v_div_scale_f32 v12, vcc, 2.0, v7, 2.0
	v_mul_f32_e32 v13, v12, v9
	v_fma_f32 v14, -v8, v13, v12
	v_fmac_f32_e32 v13, v14, v9
	v_fma_f32 v8, -v8, v13, v12
	v_div_fmas_f32 v8, v8, v9, v13
	v_div_fixup_f32 v7, v8, v7, 2.0
	v_sub_f32_e32 v7, 1.0, v7
	v_add_f32_e32 v7, 1.0, v7
	v_mul_f32_e32 v1, v1, v7
	v_cvt_pk_bf16_f32 v0, v0, v1
	v_mul_f32_e32 v1, 0x3d372713, v10
	v_mul_f32_e32 v1, v10, v1
	v_fma_f32 v1, v10, v1, v10
	v_mul_f32_e32 v1, 0x3f4c422a, v1
	v_add_f32_e32 v1, v1, v1
	v_mul_f32_e32 v1, 0x3fb8aa3b, v1
	v_exp_f32_e32 v1, v1
	s_nop 0
	v_add_f32_e32 v1, 1.0, v1
	v_div_scale_f32 v7, s[20:21], v1, v1, 2.0
	v_rcp_f32_e32 v8, v7
	s_nop 0
	v_fma_f32 v9, -v7, v8, 1.0
	v_fmac_f32_e32 v8, v9, v8
	v_div_scale_f32 v9, vcc, 2.0, v1, 2.0
	v_mul_f32_e32 v12, v9, v8
	v_fma_f32 v13, -v7, v12, v9
	v_fmac_f32_e32 v12, v13, v8
	v_fma_f32 v7, -v7, v12, v9
	v_div_fmas_f32 v7, v7, v8, v12
	v_div_fixup_f32 v1, v7, v1, 2.0
	v_sub_f32_e32 v1, 1.0, v1
	v_mul_f32_e32 v7, 0.5, v10
	v_add_f32_e32 v1, 1.0, v1
	v_mul_f32_e32 v1, v7, v1
	v_mul_f32_e32 v7, 0x3d372713, v11
	v_mul_f32_e32 v7, v11, v7
	v_fma_f32 v7, v11, v7, v11
	v_mul_f32_e32 v7, 0x3f4c422a, v7
	v_add_f32_e32 v7, v7, v7
	v_mul_f32_e32 v7, 0x3fb8aa3b, v7
	v_exp_f32_e32 v7, v7
	s_nop 0
	v_add_f32_e32 v7, 1.0, v7
	v_div_scale_f32 v8, s[20:21], v7, v7, 2.0
	v_rcp_f32_e32 v9, v8
	s_nop 0
	v_fma_f32 v10, -v8, v9, 1.0
	v_fmac_f32_e32 v9, v10, v9
	v_div_scale_f32 v10, vcc, 2.0, v7, 2.0
	v_mul_f32_e32 v12, v10, v9
	v_fma_f32 v13, -v8, v12, v10
	v_fmac_f32_e32 v12, v13, v9
	v_fma_f32 v8, -v8, v12, v10
	v_div_fmas_f32 v8, v8, v9, v12
	v_div_fixup_f32 v7, v8, v7, 2.0
	v_sub_f32_e32 v7, 1.0, v7
	v_mul_f32_e32 v8, 0.5, v11
	v_add_f32_e32 v7, 1.0, v7
	v_mul_f32_e32 v7, v8, v7
	v_cvt_pk_bf16_f32 v1, v1, v7
	v_mul_f32_e32 v7, 0x3d372713, v6
	v_mul_f32_e32 v7, v6, v7
	v_fma_f32 v7, v6, v7, v6
	v_mul_f32_e32 v7, 0x3f4c422a, v7
	v_add_f32_e32 v7, v7, v7
	v_mul_f32_e32 v7, 0x3fb8aa3b, v7
	v_exp_f32_e32 v7, v7
	v_mul_f32_e32 v6, 0.5, v6
	v_add_f32_e32 v7, 1.0, v7
	v_div_scale_f32 v8, s[20:21], v7, v7, 2.0
	v_rcp_f32_e32 v9, v8
	s_nop 0
	v_fma_f32 v10, -v8, v9, 1.0
	v_fmac_f32_e32 v9, v10, v9
	v_div_scale_f32 v10, vcc, 2.0, v7, 2.0
	v_mul_f32_e32 v11, v10, v9
	v_fma_f32 v12, -v8, v11, v10
	v_fmac_f32_e32 v11, v12, v9
	v_fma_f32 v8, -v8, v11, v10
	v_div_fmas_f32 v8, v8, v9, v11
	v_div_fixup_f32 v7, v8, v7, 2.0
	v_sub_f32_e32 v7, 1.0, v7
	v_add_f32_e32 v7, 1.0, v7
	v_mul_f32_e32 v6, v6, v7
	v_mul_f32_e32 v7, 0x3d372713, v2
	v_mul_f32_e32 v7, v2, v7
	v_fma_f32 v7, v2, v7, v2
	v_mul_f32_e32 v7, 0x3f4c422a, v7
	v_add_f32_e32 v7, v7, v7
	v_mul_f32_e32 v7, 0x3fb8aa3b, v7
	v_exp_f32_e32 v7, v7
	v_mul_f32_e32 v2, 0.5, v2
	v_add_f32_e32 v7, 1.0, v7
	v_div_scale_f32 v8, s[20:21], v7, v7, 2.0
	v_rcp_f32_e32 v9, v8
	s_nop 0
	v_fma_f32 v10, -v8, v9, 1.0
	v_fmac_f32_e32 v9, v10, v9
	v_div_scale_f32 v10, vcc, 2.0, v7, 2.0
	v_mul_f32_e32 v11, v10, v9
	v_fma_f32 v12, -v8, v11, v10
	v_fmac_f32_e32 v11, v12, v9
	v_fma_f32 v8, -v8, v11, v10
	v_div_fmas_f32 v8, v8, v9, v11
	v_div_fixup_f32 v7, v8, v7, 2.0
	v_sub_f32_e32 v7, 1.0, v7
	v_add_f32_e32 v7, 1.0, v7
	v_mul_f32_e32 v2, v2, v7
	v_cvt_pk_bf16_f32 v2, v6, v2
	v_mul_f32_e32 v6, 0x3d372713, v5
	v_mul_f32_e32 v6, v5, v6
	v_fma_f32 v6, v5, v6, v5
	v_mul_f32_e32 v6, 0x3f4c422a, v6
	v_add_f32_e32 v6, v6, v6
	v_mul_f32_e32 v6, 0x3fb8aa3b, v6
	v_exp_f32_e32 v6, v6
	v_mul_f32_e32 v5, 0.5, v5
	v_add_f32_e32 v6, 1.0, v6
	v_div_scale_f32 v7, s[20:21], v6, v6, 2.0
	v_rcp_f32_e32 v8, v7
	s_nop 0
	v_fma_f32 v9, -v7, v8, 1.0
	v_fmac_f32_e32 v8, v9, v8
	v_div_scale_f32 v9, vcc, 2.0, v6, 2.0
	v_mul_f32_e32 v10, v9, v8
	v_fma_f32 v11, -v7, v10, v9
	v_fmac_f32_e32 v10, v11, v8
	v_fma_f32 v7, -v7, v10, v9
	v_div_fmas_f32 v7, v7, v8, v10
	v_div_fixup_f32 v6, v7, v6, 2.0
	v_sub_f32_e32 v6, 1.0, v6
	v_add_f32_e32 v6, 1.0, v6
	v_mul_f32_e32 v5, v5, v6
	v_mul_f32_e32 v6, 0x3d372713, v3
	v_mul_f32_e32 v6, v3, v6
	v_fma_f32 v6, v3, v6, v3
	v_mul_f32_e32 v6, 0x3f4c422a, v6
	v_add_f32_e32 v6, v6, v6
	v_mul_f32_e32 v6, 0x3fb8aa3b, v6
	v_exp_f32_e32 v6, v6
	v_mul_f32_e32 v3, 0.5, v3
	v_add_f32_e32 v6, 1.0, v6
	v_div_scale_f32 v7, s[20:21], v6, v6, 2.0
	v_rcp_f32_e32 v8, v7
	s_nop 0
	v_fma_f32 v9, -v7, v8, 1.0
	v_fmac_f32_e32 v8, v9, v8
	v_div_scale_f32 v9, vcc, 2.0, v6, 2.0
	v_mul_f32_e32 v10, v9, v8
	v_fma_f32 v11, -v7, v10, v9
	v_fmac_f32_e32 v10, v11, v8
	v_fma_f32 v7, -v7, v10, v9
	v_div_fmas_f32 v7, v7, v8, v10
	v_div_fixup_f32 v6, v7, v6, 2.0
	v_sub_f32_e32 v6, 1.0, v6
	v_add_f32_e32 v6, 1.0, v6
	v_mul_f32_e32 v3, v3, v6
	v_cvt_pk_bf16_f32 v3, v5, v3
	v_mul_lo_u32 v5, v4, s14
	v_lshl_add_u32 v6, v35, 4, v5
	ds_write_b128 v6, v[0:3] offset:32768
	v_or_b32_e32 v0, v57, v35
	v_ashrrev_i32_e32 v1, 31, v0
	v_lshlrev_b64 v[0:1], 8, v[0:1]
	v_lshl_add_u64 v[0:1], s[12:13], 0, v[0:1]
	v_lshl_add_u64 v[14:15], v[0:1], 0, v[152:153]
	s_waitcnt lgkmcnt(0)
	s_barrier
	global_load_dwordx4 v[6:9], v[14:15], off
	global_load_dwordx4 v[10:13], v[14:15], off offset:64
	ds_read_b128 v[0:3], v16 offset:32768
	s_waitcnt vmcnt(1) lgkmcnt(0)
	v_mfma_f32_16x16x32_bf16 v[0:3], v[0:3], v[6:9], 0
	ds_read_b128 v[6:9], v16 offset:32832
	s_lshl_b32 s12, s19, 15
	s_lshl_b32 s13, s18, 14
	s_waitcnt vmcnt(0) lgkmcnt(0)
	v_mfma_f32_16x16x32_bf16 v[0:3], v[6:9], v[10:13], v[0:3]
	global_load_dwordx4 v[10:13], v[14:15], off offset:128
	ds_read_b128 v[6:9], v16 offset:32896
	s_or_b32 s14, s12, s13
	s_waitcnt vmcnt(0) lgkmcnt(0)
	v_mfma_f32_16x16x32_bf16 v[0:3], v[6:9], v[10:13], v[0:3]
	global_load_dwordx4 v[10:13], v[14:15], off offset:192
	ds_read_b128 v[6:9], v16 offset:32960
	s_mov_b64 s[12:13], -1
	s_waitcnt vmcnt(0) lgkmcnt(0)
	v_mfma_f32_16x16x32_bf16 v[0:3], v[6:9], v[10:13], v[0:3]
	v_and_b32_e32 v6, 0xffffffc0, v56
	v_lshl_add_u32 v6, v33, 10, v6
	v_or_b32_e32 v6, v6, v36
	s_and_b64 vcc, exec, s[4:5]
	s_nop 3
	ds_write2st64_b32 v6, v0, v1 offset0:160 offset1:161
	ds_write2st64_b32 v6, v2, v3 offset0:162 offset1:163
	s_waitcnt lgkmcnt(0)
	s_barrier
	s_cbranch_vccz .LBB0_346
	v_lshlrev_b32_e32 v0, 2, v56
	v_and_b32_e32 v6, 12, v0
	v_lshlrev_b32_e32 v0, 2, v32
	v_lshl_add_u32 v2, v6, 8, v0
	ds_read2st64_b32 v[0:1], v2 offset0:162 offset1:163
	ds_read2st64_b32 v[2:3], v2 offset0:160 offset1:161
	s_lshl_b32 s4, s14, 1
	v_readlane_b32 s12, v253, 36
	v_or_b32_e32 v6, s15, v6
	s_add_u32 s4, s12, s4
	v_or_b32_e32 v7, 3, v6
	s_movk_i32 s12, 0xff
	v_cmp_gt_i32_e32 vcc, s12, v7
	v_readlane_b32 s13, v253, 37
	v_ashrrev_i32_e32 v33, 31, v32
	s_waitcnt lgkmcnt(1)
	v_cndmask_b32_e32 v1, 0, v1, vcc
	s_addc_u32 s5, s13, 0
	s_waitcnt lgkmcnt(0)
	v_cvt_pk_bf16_f32 v3, v2, v3
	v_cvt_pk_bf16_f32 v2, v0, v1
	v_lshlrev_b64 v[0:1], 9, v[32:33]
	v_lshl_add_u64 v[0:1], s[4:5], 0, v[0:1]
	v_ashrrev_i32_e32 v7, 31, v6
	v_lshl_add_u64 v[0:1], v[6:7], 1, v[0:1]
	global_store_dword v[0:1], v3, off
	s_mov_b64 s[12:13], 0
